# v16 + P3 T-update reads each KA^T fragment once (into the freed att accumulators) instead of twice
# speedup vs baseline: 1.0212x; 1.0055x over previous
.Lev_skip_a:
	s_add_i32 s34, s49, 3
	v_sub_u32_e64 v32, 60, s44 clamp
	s_and_b64 s[20:21], exec, s[38:39]
	v_readfirstlane_b32 s20, v32
	s_cselect_b32 s66, s34, s20
	s_lshl_b32 s34, s66, 13
	s_lshl_b32 s67, s66, 14
	s_add_u32 s20, s43, s67
	s_addc_u32 s21, s63, 0
	v_lshl_add_u64 v[36:37], s[20:21], 0, v[120:121]
	global_load_dwordx4 v[32:35], v120, s[20:21]
	v_add_co_u32_e64 v36, s[20:21], s60, v36
	v_lshl_add_u64 v[48:49], v[146:147], 0, s[34:35]
	s_nop 0
	v_addc_co_u32_e64 v37, s[20:21], 0, v37, s[20:21]
	s_add_u32 s20, s64, s67
	s_addc_u32 s21, s65, 0
	v_lshl_add_u64 v[44:45], s[20:21], 0, v[120:121]
	global_load_dwordx4 v[36:39], v[36:37], off
	s_lshl_b32 s34, s66, 10
	global_load_dwordx4 v[40:43], v120, s[20:21]
	v_add_co_u32_e64 v44, s[20:21], s60, v44
	v_lshl_add_u64 v[52:53], v[148:149], 0, s[34:35]
	s_nop 0
	v_addc_co_u32_e64 v45, s[20:21], 0, v45, s[20:21]
	s_lshl_b32 s20, s49, 1
	s_add_i32 s34, s20, 4
	s_waitcnt vmcnt(15)
	v_mov_b32_e32 v214, v64
	v_mov_b32_e32 v215, v65
	v_mov_b32_e32 v216, v66
	v_mov_b32_e32 v217, v67
	v_lshl_add_u64 v[64:65], v[144:145], 0, s[34:35]
	s_add_i32 s34, 0, 0x1e400
	v_mov_b32_e32 v198, v56
	v_mov_b32_e32 v199, v57
	v_mov_b32_e32 v200, v58
	v_mov_b32_e32 v201, v59
	v_mov_b32_e32 v202, v60
	v_mov_b32_e32 v203, v61
	v_mov_b32_e32 v204, v62
	v_mov_b32_e32 v205, v63
	s_waitcnt vmcnt(14)
	v_mov_b32_e32 v242, v68
	v_mov_b32_e32 v243, v69
	v_mov_b32_e32 v244, v70
	v_mov_b32_e32 v245, v71
	v_add_u32_e32 v116, s34, v143
	ds_read_b128 v[190:193], v116
	v_and_b32_e32 v66, 0xfff, v64
	v_cmp_ne_u32_e64 s[20:21], 0, v66
	v_add_u32_e32 v185, 0, v143
	v_add_u32_e32 v116, 0x1e600, v185
	s_waitcnt lgkmcnt(0)
	v_pk_mul_f32 v[192:193], v[98:99], v[192:193]
	v_pk_mul_f32 v[190:191], v[96:97], v[190:191]
	v_pk_mul_f32 v[98:99], v[102:103], v[192:193]
	v_pk_mul_f32 v[96:97], v[100:101], v[190:191]
	v_cndmask_b32_e64 v56, 0, 1, s[20:21]
	v_cvt_pk_bf16_f32 v100, v96, v97
	v_cvt_pk_bf16_f32 v101, v98, v99
	v_sub_co_u32_e64 v56, s[20:21], v64, v56
	ds_read_b128 v[116:119], v116
	ds_write_b64 v182, v[100:101]
	v_pk_mul_f32 v[100:101], v[104:105], v[190:191]
	v_pk_mul_f32 v[102:103], v[106:107], v[192:193]
	v_subbrev_co_u32_e64 v57, s[20:21], 0, v65, s[20:21]
	v_cvt_pk_bf16_f32 v104, v100, v101
	v_cvt_pk_bf16_f32 v105, v102, v103
	v_cmp_ne_u32_e64 s[20:21], s62, v66
	ds_write_b64 v182, v[104:105] offset:4352
	v_pk_mul_f32 v[104:105], v[108:109], v[190:191]
	v_pk_mul_f32 v[106:107], v[110:111], v[192:193]
	v_cndmask_b32_e64 v66, 0, 1, s[20:21]
	v_mov_b32_e32 v67, s35
	v_cvt_pk_bf16_f32 v108, v104, v105
	v_cvt_pk_bf16_f32 v109, v106, v107
	v_lshlrev_b64 v[68:69], 11, v[64:65]
	v_lshl_add_u64 v[64:65], v[64:65], 0, v[66:67]
	ds_write_b64 v182, v[108:109] offset:8704
	v_pk_mul_f32 v[108:109], v[112:113], v[190:191]
	v_pk_mul_f32 v[110:111], v[114:115], v[192:193]
	v_lshlrev_b64 v[56:57], 11, v[56:57]
	v_lshlrev_b64 v[64:65], 11, v[64:65]
	v_cvt_pk_bf16_f32 v112, v108, v109
	v_cvt_pk_bf16_f32 v113, v110, v111
	v_lshl_add_u64 v[56:57], v[134:135], 0, v[56:57]
	v_lshl_add_u64 v[60:61], v[134:135], 0, v[68:69]
	v_lshl_add_u64 v[64:65], v[134:135], 0, v[64:65]
	v_lshl_add_u64 v[68:69], v[136:137], 0, v[68:69]
	ds_write_b64 v182, v[112:113] offset:13056
	global_load_dwordx4 v[44:47], v[44:45], off
	global_load_dwordx4 v[48:51], v[48:49], off
	global_load_dwordx4 v[52:55], v[52:53], off
	global_load_dwordx4 v[56:59], v[56:57], off
	s_lshl_b32 s48, s48, 6
	global_load_dwordx4 v[60:63], v[60:61], off
	s_nop 0
	global_load_dwordx4 v[64:67], v[64:65], off
	s_nop 0
	global_load_dwordx4 v[68:71], v[68:69], off
	s_waitcnt lgkmcnt(0)
	s_barrier
	ds_read_b128 v[218:221], v170 offset:61440
	ds_read_b128 v[222:225], v171 offset:44032
	ds_read_b128 v[226:229], v172 offset:44032
	ds_read_b128 v[230:233], v170 offset:61504
	ds_read_b128 v[234:237], v171 offset:44096
	ds_read_b128 v[238:241], v172 offset:44096
	v_and_b32_e32 v250, 0xfff, v184
	v_cmp_ne_u32_e64 s[20:21], 0, v250
	v_add_u32_e32 v184, 4, v184
	v_cndmask_b32_e64 v198, 0, v198, s[20:21]
	v_cndmask_b32_e64 v199, 0, v199, s[20:21]
	v_cndmask_b32_e64 v200, 0, v200, s[20:21]
	v_cndmask_b32_e64 v201, 0, v201, s[20:21]
	v_cmp_ne_u32_e64 s[20:21], s62, v250
	v_lshlrev_b32_e32 v246, 16, v202
	v_and_b32_e32 v247, 0xffff0000, v202
	v_cndmask_b32_e64 v214, 0, v214, s[20:21]
	v_cndmask_b32_e64 v215, 0, v215, s[20:21]
	v_cndmask_b32_e64 v216, 0, v216, s[20:21]
	v_cndmask_b32_e64 v217, 0, v217, s[20:21]
	v_pk_mul_f32 v[246:247], v[8:9], v[246:247]
	v_lshlrev_b32_e32 v248, 16, v198
	v_and_b32_e32 v249, 0xffff0000, v198
	v_pk_fma_f32 v[246:247], v[0:1], v[248:249], v[246:247]
	v_lshlrev_b32_e32 v248, 16, v214
	v_and_b32_e32 v249, 0xffff0000, v214
	v_pk_fma_f32 v[246:247], v[16:17], v[248:249], v[246:247]
	v_pk_add_f32 v[246:247], v[24:25], v[246:247]
	v_lshlrev_b32_e32 v248, 16, v242
	v_and_b32_e32 v249, 0xffff0000, v242
	v_pk_mul_f32 v[246:247], v[246:247], v[248:249]
	v_cvt_pk_bf16_f32 v198, v246, v247
	v_lshlrev_b32_e32 v246, 16, v203
	v_and_b32_e32 v247, 0xffff0000, v203
	v_pk_mul_f32 v[246:247], v[10:11], v[246:247]
	v_lshlrev_b32_e32 v248, 16, v199
	v_and_b32_e32 v249, 0xffff0000, v199
	v_pk_fma_f32 v[246:247], v[2:3], v[248:249], v[246:247]
	v_lshlrev_b32_e32 v248, 16, v215
	v_and_b32_e32 v249, 0xffff0000, v215
	v_pk_fma_f32 v[246:247], v[18:19], v[248:249], v[246:247]
	v_pk_add_f32 v[246:247], v[26:27], v[246:247]
	v_lshlrev_b32_e32 v248, 16, v243
	v_and_b32_e32 v249, 0xffff0000, v243
	v_pk_mul_f32 v[246:247], v[246:247], v[248:249]
	v_cvt_pk_bf16_f32 v199, v246, v247
	v_lshlrev_b32_e32 v246, 16, v204
	v_and_b32_e32 v247, 0xffff0000, v204
	v_pk_mul_f32 v[246:247], v[12:13], v[246:247]
	v_lshlrev_b32_e32 v248, 16, v200
	v_and_b32_e32 v249, 0xffff0000, v200
	v_pk_fma_f32 v[246:247], v[4:5], v[248:249], v[246:247]
	v_lshlrev_b32_e32 v248, 16, v216
	v_and_b32_e32 v249, 0xffff0000, v216
	v_pk_fma_f32 v[246:247], v[20:21], v[248:249], v[246:247]
	v_pk_add_f32 v[246:247], v[28:29], v[246:247]
	v_lshlrev_b32_e32 v248, 16, v244
	v_and_b32_e32 v249, 0xffff0000, v244
	v_pk_mul_f32 v[246:247], v[246:247], v[248:249]
	v_cvt_pk_bf16_f32 v200, v246, v247
	v_lshlrev_b32_e32 v246, 16, v205
	v_and_b32_e32 v247, 0xffff0000, v205
	v_pk_mul_f32 v[246:247], v[14:15], v[246:247]
	v_lshlrev_b32_e32 v248, 16, v201
	v_and_b32_e32 v249, 0xffff0000, v201
	v_pk_fma_f32 v[246:247], v[6:7], v[248:249], v[246:247]
	v_lshlrev_b32_e32 v248, 16, v217
	v_and_b32_e32 v249, 0xffff0000, v217
	v_pk_fma_f32 v[246:247], v[22:23], v[248:249], v[246:247]
	v_pk_add_f32 v[246:247], v[30:31], v[246:247]
	v_lshlrev_b32_e32 v248, 16, v245
	v_and_b32_e32 v249, 0xffff0000, v245
	v_pk_mul_f32 v[246:247], v[246:247], v[248:249]
	v_cvt_pk_bf16_f32 v201, v246, v247
	global_store_dwordx4 v[152:153], v[198:201], off
	ds_read_b128 v[242:245], v170 offset:61568
	ds_read_b128 v[246:249], v171 offset:44160
	ds_read_b128 v[250:253], v172 offset:44160
	s_waitcnt lgkmcnt(6)
	v_mfma_f32_16x16x32_bf16 v[190:193], v[218:221], v[222:225], 0
	v_mfma_f32_16x16x32_bf16 v[194:197], v[218:221], v[226:229], 0
	ds_read_b128 v[218:221], v170 offset:61632
	ds_read_b128 v[222:225], v171 offset:44224
	ds_read_b128 v[226:229], v172 offset:44224
	s_waitcnt lgkmcnt(6)
	v_mfma_f32_16x16x32_bf16 v[190:193], v[230:233], v[234:237], v[190:193]
	v_mfma_f32_16x16x32_bf16 v[194:197], v[230:233], v[238:241], v[194:197]
	ds_read_b64_tr_b16 v[230:231], v206 offset:34816
	ds_read_b64_tr_b16 v[232:233], v206 offset:35392
	ds_read_b128 v[234:237], v208
	ds_read_b128 v[238:241], v209
	s_waitcnt lgkmcnt(7)
	v_mfma_f32_16x16x32_bf16 v[190:193], v[242:245], v[246:249], v[190:193]
	v_mfma_f32_16x16x32_bf16 v[194:197], v[242:245], v[250:253], v[194:197]
	ds_read_b64_tr_b16 v[242:243], v206 offset:39424
	ds_read_b64_tr_b16 v[244:245], v206 offset:40000
	ds_read_b128 v[246:249], v208 offset:64
	ds_read_b128 v[250:253], v209 offset:64
	s_waitcnt lgkmcnt(8)
	v_mfma_f32_16x16x32_bf16 v[190:193], v[218:221], v[222:225], v[190:193]
	v_mfma_f32_16x16x32_bf16 v[194:197], v[218:221], v[226:229], v[194:197]
	ds_read_b128 v[218:221], v183
	ds_read_b128 v[222:225], v171
	ds_read_b128 v[226:229], v172
	s_waitcnt lgkmcnt(7)
	v_mfma_f32_16x16x32_bf16 v[198:201], v[230:233], v[234:237], 0
	v_mfma_f32_16x16x32_bf16 v[202:205], v[230:233], v[238:241], 0
	ds_read_b128 v[230:233], v183 offset:64
	ds_read_b128 v[234:237], v171 offset:64
	ds_read_b128 v[238:241], v172 offset:64
	s_waitcnt lgkmcnt(6)
	v_mfma_f32_16x16x32_bf16 v[198:201], v[242:245], v[246:249], v[198:201]
	v_mfma_f32_16x16x32_bf16 v[202:205], v[242:245], v[250:253], v[202:205]
	ds_read_b128 v[242:245], v183 offset:128
	ds_read_b128 v[246:249], v171 offset:128
	ds_read_b128 v[250:253], v172 offset:128
	v_cndmask_b32_e32 v190, 0, v190, vcc
	v_cndmask_b32_e64 v191, 0, v191, s[6:7]
	v_cndmask_b32_e64 v192, 0, v192, s[8:9]
	v_cndmask_b32_e64 v193, 0, v193, s[10:11]
	v_cvt_pk_bf16_f32 v190, v190, v191
	v_cvt_pk_bf16_f32 v191, v192, v193
	v_cndmask_b32_e64 v194, 0, v194, s[12:13]
	v_cndmask_b32_e64 v195, 0, v195, s[14:15]
	v_cndmask_b32_e64 v196, 0, v196, s[16:17]
	v_cndmask_b32_e64 v197, 0, v197, s[18:19]
	v_cvt_pk_bf16_f32 v194, v194, v195
	v_cvt_pk_bf16_f32 v195, v196, v197
	ds_write_b64 v212, v[190:191]
	ds_write_b64 v213, v[194:195]
	s_waitcnt lgkmcnt(8)
	v_mfma_f32_16x16x32_bf16 v[198:201], v[218:221], v[222:225], v[198:201]
	v_mfma_f32_16x16x32_bf16 v[202:205], v[218:221], v[226:229], v[202:205]
	ds_read_b64_tr_b16 v[190:191], v178 offset:17408
	ds_read_b64_tr_b16 v[192:193], v178 offset:18496
	ds_read_b64_tr_b16 v[194:195], v178 offset:26112
	ds_read_b64_tr_b16 v[196:197], v178 offset:27200
	s_waitcnt lgkmcnt(9)
	v_mfma_f32_16x16x32_bf16 v[198:201], v[230:233], v[234:237], v[198:201]
	v_mfma_f32_16x16x32_bf16 v[202:205], v[230:233], v[238:241], v[202:205]
	ds_read_b128 v[230:233], v183 offset:192
	ds_read_b128 v[234:237], v171 offset:192
	ds_read_b128 v[238:241], v172 offset:192
	s_waitcnt lgkmcnt(9)
	v_mfma_f32_16x16x32_bf16 v[198:201], v[242:245], v[246:249], v[198:201]
	v_mfma_f32_16x16x32_bf16 v[202:205], v[242:245], v[250:253], v[202:205]
	ds_read_b64_tr_b16 v[242:243], v161 offset:34816
	ds_read_b64_tr_b16 v[244:245], v161 offset:35392
	ds_read_b64_tr_b16 v[246:247], v161 offset:34848
	ds_read_b64_tr_b16 v[248:249], v161 offset:35424
	s_waitcnt lgkmcnt(7)
	ds_read_b64_tr_b16 v[218:219], v161 offset:34880
	ds_read_b64_tr_b16 v[220:221], v161 offset:35456
	ds_read_b64_tr_b16 v[222:223], v161 offset:34912
	ds_read_b64_tr_b16 v[224:225], v161 offset:35488
	s_waitcnt lgkmcnt(8)
	v_mfma_f32_16x16x32_bf16 v[198:201], v[230:233], v[234:237], v[198:201]
	v_mfma_f32_16x16x32_bf16 v[202:205], v[230:233], v[238:241], v[202:205]
	ds_read_b64_tr_b16 v[230:231], v161 offset:39424
	ds_read_b64_tr_b16 v[232:233], v161 offset:40000
	ds_read_b64_tr_b16 v[234:235], v161 offset:39456
	ds_read_b64_tr_b16 v[236:237], v161 offset:40032
	s_waitcnt lgkmcnt(8)
	v_mfma_f32_16x16x32_bf16 v[96:99], v[190:193], v[242:245], v[96:99]
	v_mfma_f32_16x16x32_bf16 v[100:103], v[190:193], v[246:249], v[100:103]
	ds_read_b64_tr_b16 v[242:243], v161 offset:39488
	ds_read_b64_tr_b16 v[244:245], v161 offset:40064
	ds_read_b64_tr_b16 v[246:247], v161 offset:39520
	ds_read_b64_tr_b16 v[248:249], v161 offset:40096
	v_cvt_pk_bf16_f32 v198, v198, v199
	v_cvt_pk_bf16_f32 v199, v200, v201
	v_add_u32_e32 v254, s48, v173
	v_mad_u64_u32 v[254:255], s[20:21], v254, s42, 0
	v_lshl_add_u64 v[254:255], v[254:255], 1, v[150:151]
	v_cvt_pk_bf16_f32 v202, v202, v203
	v_cvt_pk_bf16_f32 v203, v204, v205
	global_store_dwordx2 v[254:255], v[198:199], off
	v_add_u32_e32 v254, s48, v179
	v_mad_u64_u32 v[254:255], s[20:21], v254, s42, 0
	v_lshl_add_u64 v[254:255], v[254:255], 1, v[150:151]
	global_store_dwordx2 v[254:255], v[202:203], off
	s_waitcnt lgkmcnt(8)
	v_mfma_f32_16x16x32_bf16 v[104:107], v[190:193], v[218:221], v[104:107]
	v_mfma_f32_16x16x32_bf16 v[214:217], v[190:193], v[222:225], v[108:111]
	s_waitcnt lgkmcnt(4)
	v_mfma_f32_16x16x32_bf16 v[112:115], v[194:197], v[230:233], v[96:99]
	v_mfma_f32_16x16x32_bf16 v[108:111], v[194:197], v[234:237], v[100:103]
	s_waitcnt lgkmcnt(0)
	v_mfma_f32_16x16x32_bf16 v[104:107], v[194:197], v[242:245], v[104:107]
	v_mfma_f32_16x16x32_bf16 v[100:103], v[194:197], v[246:249], v[214:217]
	s_min_u32 s20, s44, 59
	s_waitcnt lgkmcnt(0)
	s_barrier
	s_waitcnt vmcnt(20)
	ds_write_b128 v168, v[72:75]
	s_waitcnt vmcnt(19)
	ds_write_b128 v168, v[80:83] offset:8704
	s_waitcnt vmcnt(18)
	ds_write_b128 v168, v[76:79] offset:17408
	s_waitcnt vmcnt(17)
	ds_write_b128 v168, v[84:87] offset:26112
	s_waitcnt vmcnt(16)
	ds_write_b128 v169, v[88:91] offset:34816
	v_add_u32_e32 v72, s34, v154
	s_add_i32 s34, s20, 4
	s_waitcnt vmcnt(15)
	s_cmp_lg_u32 s69, 0
	s_cbranch_scc1 .Lev_skip_b
	ds_write_b128 v72, v[92:95]
.Lev_skip_b:
	v_sub_u32_e64 v72, 59, s44 clamp
	s_and_b64 s[20:21], exec, s[38:39]
	v_readfirstlane_b32 s20, v72
	s_cselect_b32 s48, s34, s20
	v_add_u32_e32 v96, s61, v143
	s_lshl_b32 s34, s48, 13
	s_lshl_b32 s49, s48, 14
	ds_read_b128 v[186:189], v96
	s_add_u32 s20, s43, s49
	s_addc_u32 s21, s63, 0
	v_lshl_add_u64 v[76:77], s[20:21], 0, v[120:121]
	global_load_dwordx4 v[72:75], v120, s[20:21]
	v_add_co_u32_e64 v76, s[20:21], s60, v76
	s_waitcnt lgkmcnt(0)
	v_pk_mul_f32 v[118:119], v[118:119], v[188:189]
	v_addc_co_u32_e64 v77, s[20:21], 0, v77, s[20:21]
	v_pk_mul_f32 v[116:117], v[116:117], v[186:187]
	s_add_u32 s20, s64, s49
	v_pk_mul_f32 v[114:115], v[114:115], v[118:119]
	v_pk_mul_f32 v[112:113], v[112:113], v[116:117]
	s_addc_u32 s21, s65, 0
	v_add_u32_e32 v96, 0x1ea00, v185
	v_cvt_pk_bf16_f32 v186, v112, v113
	v_cvt_pk_bf16_f32 v187, v114, v115
	v_pk_mul_f32 v[110:111], v[110:111], v[118:119]
	v_pk_mul_f32 v[108:109], v[108:109], v[116:117]
	v_lshl_add_u64 v[84:85], s[20:21], 0, v[120:121]
	ds_read_b128 v[96:99], v96
	ds_write_b64 v182, v[186:187]
	v_cvt_pk_bf16_f32 v186, v108, v109
	v_cvt_pk_bf16_f32 v187, v110, v111
	v_pk_mul_f32 v[106:107], v[106:107], v[118:119]
	v_pk_mul_f32 v[104:105], v[104:105], v[116:117]
	v_pk_mul_f32 v[102:103], v[102:103], v[118:119]
	v_pk_mul_f32 v[100:101], v[100:101], v[116:117]
	global_load_dwordx4 v[80:83], v[76:77], off
	v_lshl_add_u64 v[88:89], v[146:147], 0, s[34:35]
	global_load_dwordx4 v[76:79], v120, s[20:21]
	v_add_co_u32_e64 v84, s[20:21], s60, v84
	s_lshl_b32 s34, s48, 10
	ds_write_b64 v182, v[186:187] offset:4352
	v_cvt_pk_bf16_f32 v186, v104, v105
	v_cvt_pk_bf16_f32 v187, v106, v107
	v_cvt_pk_bf16_f32 v116, v100, v101
	v_cvt_pk_bf16_f32 v117, v102, v103
	v_addc_co_u32_e64 v85, s[20:21], 0, v85, s[20:21]
	v_lshl_add_u64 v[92:93], v[148:149], 0, s[34:35]
	ds_write_b64 v182, v[186:187] offset:8704
	ds_write_b64 v182, v[116:117] offset:13056
	global_load_dwordx4 v[84:87], v[84:85], off
	v_add_u32_e32 v185, s31, v162
	global_load_dwordx4 v[88:91], v[88:89], off
	v_add_u32_e32 v194, s45, v159
	global_load_dwordx4 v[92:95], v[92:93], off
	s_waitcnt lgkmcnt(0)
	s_barrier
	ds_read_b128 v[218:221], v170 offset:17408
	ds_read_b128 v[222:225], v171
	ds_read_b128 v[226:229], v172
	ds_read_b128 v[230:233], v170 offset:17472
	ds_read_b128 v[234:237], v171 offset:64
	ds_read_b128 v[238:241], v172 offset:64
	ds_read_b128 v[242:245], v170 offset:17536
	ds_read_b128 v[246:249], v171 offset:128
	ds_read_b128 v[250:253], v172 offset:128
	s_add_i32 s34, s44, 1
	s_and_b64 s[20:21], exec, s[38:39]
	s_cselect_b32 s20, s34, s47
	s_lshl_b32 s34, s20, 6
	s_add_i32 s47, s47, -2
	v_lshl_add_u64 v[152:153], v[152:153], 0, s[36:37]
	s_waitcnt lgkmcnt(6)
	v_mfma_f32_16x16x32_bf16 v[190:193], v[218:221], v[222:225], 0
	v_mfma_f32_16x16x32_bf16 v[194:197], v[218:221], v[226:229], 0
	ds_read_b128 v[218:221], v170 offset:17600
	ds_read_b128 v[222:225], v171 offset:192
	ds_read_b128 v[226:229], v172 offset:192
	s_waitcnt lgkmcnt(6)
	v_mfma_f32_16x16x32_bf16 v[190:193], v[230:233], v[234:237], v[190:193]
	v_mfma_f32_16x16x32_bf16 v[194:197], v[230:233], v[238:241], v[194:197]
	ds_read_b64_tr_b16 v[230:231], v207
	ds_read_b64_tr_b16 v[232:233], v207 offset:576
	ds_read_b128 v[234:237], v210
	ds_read_b128 v[238:241], v211
	s_waitcnt lgkmcnt(7)
	v_mfma_f32_16x16x32_bf16 v[190:193], v[242:245], v[246:249], v[190:193]
	v_mfma_f32_16x16x32_bf16 v[194:197], v[242:245], v[250:253], v[194:197]
	ds_read_b64_tr_b16 v[242:243], v207 offset:4608
	ds_read_b64_tr_b16 v[244:245], v207 offset:5184
	ds_read_b128 v[246:249], v210 offset:64
	ds_read_b128 v[250:253], v211 offset:64
	s_waitcnt lgkmcnt(8)
	v_mfma_f32_16x16x32_bf16 v[190:193], v[218:221], v[222:225], v[190:193]
	v_mfma_f32_16x16x32_bf16 v[194:197], v[218:221], v[226:229], v[194:197]
	ds_read_b128 v[218:221], v183
	ds_read_b128 v[222:225], v171 offset:44032
	ds_read_b128 v[226:229], v172 offset:44032
	s_waitcnt lgkmcnt(7)
	v_mfma_f32_16x16x32_bf16 v[198:201], v[230:233], v[234:237], 0
	v_mfma_f32_16x16x32_bf16 v[202:205], v[230:233], v[238:241], 0
	ds_read_b128 v[230:233], v183 offset:64
	ds_read_b128 v[234:237], v171 offset:44096
	ds_read_b128 v[238:241], v172 offset:44096
	s_waitcnt lgkmcnt(6)
	v_mfma_f32_16x16x32_bf16 v[198:201], v[242:245], v[246:249], v[198:201]
	v_mfma_f32_16x16x32_bf16 v[202:205], v[242:245], v[250:253], v[202:205]
	ds_read_b128 v[242:245], v183 offset:128
	ds_read_b128 v[246:249], v171 offset:44160
	ds_read_b128 v[250:253], v172 offset:44160
	v_cndmask_b32_e32 v190, 0, v190, vcc
	v_cndmask_b32_e64 v191, 0, v191, s[6:7]
	v_cndmask_b32_e64 v192, 0, v192, s[8:9]
	v_cndmask_b32_e64 v193, 0, v193, s[10:11]
	v_cvt_pk_bf16_f32 v190, v190, v191
	v_cvt_pk_bf16_f32 v191, v192, v193
	v_cndmask_b32_e64 v194, 0, v194, s[12:13]
	v_cndmask_b32_e64 v195, 0, v195, s[14:15]
	v_cndmask_b32_e64 v196, 0, v196, s[16:17]
	v_cndmask_b32_e64 v197, 0, v197, s[18:19]
	v_cvt_pk_bf16_f32 v194, v194, v195
	v_cvt_pk_bf16_f32 v195, v196, v197
	ds_write_b64 v175, v[190:191]
	ds_write_b64 v177, v[194:195]
	s_waitcnt lgkmcnt(8)
	v_mfma_f32_16x16x32_bf16 v[198:201], v[218:221], v[222:225], v[198:201]
	v_mfma_f32_16x16x32_bf16 v[202:205], v[218:221], v[226:229], v[202:205]
	ds_read_b64_tr_b16 v[190:191], v178 offset:61440
	ds_read_b64_tr_b16 v[192:193], v178 offset:62528
	ds_read_b64_tr_b16 v[194:195], v181 offset:8704
	ds_read_b64_tr_b16 v[196:197], v181 offset:9792
	s_waitcnt lgkmcnt(9)
	v_mfma_f32_16x16x32_bf16 v[198:201], v[230:233], v[234:237], v[198:201]
	v_mfma_f32_16x16x32_bf16 v[202:205], v[230:233], v[238:241], v[202:205]
	ds_read_b128 v[230:233], v183 offset:192
	ds_read_b128 v[234:237], v171 offset:44224
	ds_read_b128 v[238:241], v172 offset:44224
	s_waitcnt lgkmcnt(9)
	v_mfma_f32_16x16x32_bf16 v[198:201], v[242:245], v[246:249], v[198:201]
	v_mfma_f32_16x16x32_bf16 v[202:205], v[242:245], v[250:253], v[202:205]
	ds_read_b64_tr_b16 v[242:243], v162
	ds_read_b64_tr_b16 v[244:245], v162 offset:576
	ds_read_b64_tr_b16 v[246:247], v162 offset:32
	ds_read_b64_tr_b16 v[248:249], v162 offset:608
	s_waitcnt lgkmcnt(7)
	ds_read_b64_tr_b16 v[218:219], v162 offset:64
	ds_read_b64_tr_b16 v[220:221], v162 offset:640
	ds_read_b64_tr_b16 v[222:223], v162 offset:96
	ds_read_b64_tr_b16 v[224:225], v162 offset:672
	s_waitcnt lgkmcnt(8)
	v_mfma_f32_16x16x32_bf16 v[198:201], v[230:233], v[234:237], v[198:201]
	v_mfma_f32_16x16x32_bf16 v[202:205], v[230:233], v[238:241], v[202:205]
	ds_read_b64_tr_b16 v[230:231], v162 offset:4608
	ds_read_b64_tr_b16 v[232:233], v162 offset:5184
	ds_read_b64_tr_b16 v[234:235], v162 offset:4640
	ds_read_b64_tr_b16 v[236:237], v162 offset:5216
	s_waitcnt lgkmcnt(8)
	v_mfma_f32_16x16x32_bf16 v[112:115], v[190:193], v[242:245], v[112:115]
	v_mfma_f32_16x16x32_bf16 v[108:111], v[190:193], v[246:249], v[108:111]
	ds_read_b64_tr_b16 v[242:243], v162 offset:4672
	ds_read_b64_tr_b16 v[244:245], v162 offset:5248
	ds_read_b64_tr_b16 v[246:247], v162 offset:4704
	ds_read_b64_tr_b16 v[248:249], v162 offset:5280
	v_cvt_pk_bf16_f32 v198, v198, v199
	v_cvt_pk_bf16_f32 v199, v200, v201
	v_add_u32_e32 v254, s34, v173
	v_mad_u64_u32 v[254:255], s[20:21], v254, s42, 0
	v_lshl_add_u64 v[254:255], v[254:255], 1, v[150:151]
	v_cvt_pk_bf16_f32 v202, v202, v203
	v_cvt_pk_bf16_f32 v203, v204, v205
	global_store_dwordx2 v[254:255], v[198:199], off
	v_add_u32_e32 v254, s34, v179
	v_mad_u64_u32 v[254:255], s[20:21], v254, s42, 0
	v_lshl_add_u64 v[254:255], v[254:255], 1, v[150:151]
	global_store_dwordx2 v[254:255], v[202:203], off
	s_waitcnt lgkmcnt(8)
	v_mfma_f32_16x16x32_bf16 v[214:217], v[190:193], v[218:221], v[104:107]
	v_mfma_f32_16x16x32_bf16 v[116:119], v[190:193], v[222:225], v[100:103]
	s_waitcnt lgkmcnt(4)
	v_mfma_f32_16x16x32_bf16 v[100:103], v[194:197], v[230:233], v[112:115]
	v_mfma_f32_16x16x32_bf16 v[104:107], v[194:197], v[234:237], v[108:111]
	s_waitcnt lgkmcnt(0)
	v_mfma_f32_16x16x32_bf16 v[108:111], v[194:197], v[242:245], v[214:217]
	v_mfma_f32_16x16x32_bf16 v[112:115], v[194:197], v[246:249], v[116:119]
	s_add_i32 s20, s44, 2
	s_cmp_lt_u32 s44, 62
	s_mov_b32 s44, s20
	s_waitcnt lgkmcnt(0)
	s_barrier
	s_cbranch_scc1 .LBB0_350
	s_add_i32 s30, s30, s28
	v_lshl_add_u64 v[140:141], v[140:141], 0, s[26:27]
	s_cmpk_lt_i32 s30, 0x100
	v_add_u32_e32 v165, s29, v165
	s_cbranch_scc1 .LBB0_344
